# retention output phase: the state-fragment loads of k-steps 1-4 (12 loads each issued one at a time behind vmcnt(0)) are now issued four at a time into separate registers one k-step ahead
# speedup vs baseline: 1.0088x; 1.0088x over previous
; #define LAS __attribute__((address_space(3)))
; __device__ __forceinline__ void ret_out_phase(int j, LAS unsigned char* lds, int tid, int lane, int wave, int dry) { KARGS;
;     ...
;         const bf16_t* sp = ST + ((size_t)(cs * 8 + h) * 512 + 64 * wave + fr) * 256 + 8 * fq;
;         bf16x8 af[2][4];
; #pragma unroll
;         for (int et = 0; et < 4; ++et) af[0][et] = *(const bf16x8*)(sp + (size_t)et * 16 * 256);
;         __syncthreads();
;         f32x4 acc[4][4];
; #pragma unroll
;         for (int et = 0; et < 4; ++et)
; #pragma unroll
;             for (int lt = 0; lt < 4; ++lt) acc[et][lt] = (f32x4){0.f, 0.f, 0.f, 0.f};
;         {
; #pragma unroll
;             for (int ks = 0; ks < 8; ++ks) {
;                 if (ks < 7) {
; #pragma unroll
;                     for (int et = 0; et < 4; ++et) af[(ks + 1) & 1][et] = *(const bf16x8*)(sp + (size_t)et * 16 * 256 + 32 * (ks + 1));
;                 }
;                 bf16x8 qf[4];
; #pragma unroll
;                 for (int lt = 0; lt < 4; ++lt) qf[lt] = *(const LAS bf16x8*)(Ql + (16 * lt + fr) * QPITCH + (32 * ks + 8 * fq) * 2);
; #pragma unroll
;                 for (int et = 0; et < 4; ++et)
; #pragma unroll
;                     for (int lt = 0; lt < 4; ++lt) acc[et][lt] = __builtin_amdgcn_mfma_f32_16x16x32_bf16(af[ks & 1][et], qf[lt], acc[et][lt], 0, 0, 0);
;             }
.LBB0_777:
	v_readfirstlane_b32 s4, v22
	s_sub_i32 s4, s13, s4
	s_lshl_b32 s4, s4, 3
	s_or_b32 s4, s4, s16
	s_ashr_i32 s5, s4, 31
	s_lshl_b64 s[4:5], s[4:5], 18
	v_lshl_add_u64 v[68:69], v[118:119], 0, s[4:5]
	v_add_co_u32_e32 v130, vcc, 0x2000, v68
	global_load_dwordx4 v[16:19], v[68:69], off
	s_nop 0
	v_addc_co_u32_e32 v131, vcc, 0, v69, vcc
	v_add_co_u32_e32 v128, vcc, 0x4000, v68
	global_load_dwordx4 v[20:23], v[130:131], off
	s_nop 0
	v_addc_co_u32_e32 v129, vcc, 0, v69, vcc
	v_add_co_u32_e32 v126, vcc, 0x6000, v68
	global_load_dwordx4 v[24:27], v[128:129], off
	s_nop 0
	v_addc_co_u32_e32 v127, vcc, 0, v69, vcc
	global_load_dwordx4 v[28:31], v[126:127], off
	s_waitcnt lgkmcnt(0)
	s_barrier
	global_load_dwordx4 v[86:89], v[68:69], off offset:64
	global_load_dwordx4 v[242:245], v[130:131], off offset:64
	global_load_dwordx4 v[246:249], v[128:129], off offset:64
	global_load_dwordx4 v[250:253], v[126:127], off offset:64
	ds_read_b128 v[32:35], v217
	ds_read_b128 v[138:141], v217 offset:384
	ds_read_b128 v[40:43], v217 offset:8448
	ds_read_b128 v[142:145], v217 offset:8832
	ds_read_b128 v[48:51], v217 offset:16896
	ds_read_b128 v[94:97], v217 offset:16960
	ds_read_b128 v[56:59], v236
	ds_read_b128 v[98:101], v236 offset:64
	s_ashr_i32 s13, s12, 31
	s_lshl_b64 s[4:5], s[12:13], 16
	s_waitcnt vmcnt(7) lgkmcnt(7)
	v_mfma_f32_16x16x32_bf16 v[36:39], v[16:19], v[32:35], 0
	ds_read_b128 v[90:93], v217 offset:8512
	ds_read_b128 v[146:149], v217 offset:17280
	s_waitcnt lgkmcnt(7)
	v_mfma_f32_16x16x32_bf16 v[44:47], v[16:19], v[40:43], 0
	s_waitcnt lgkmcnt(5)
	v_mfma_f32_16x16x32_bf16 v[52:55], v[16:19], v[48:51], 0
	s_waitcnt lgkmcnt(3)
	v_mfma_f32_16x16x32_bf16 v[16:19], v[16:19], v[56:59], 0
	s_waitcnt vmcnt(6)
	v_mfma_f32_16x16x32_bf16 v[60:63], v[20:23], v[32:35], 0
	v_mfma_f32_16x16x32_bf16 v[64:67], v[20:23], v[40:43], 0
	v_mfma_f32_16x16x32_bf16 v[70:73], v[20:23], v[48:51], 0
	v_mfma_f32_16x16x32_bf16 v[20:23], v[20:23], v[56:59], 0
	s_waitcnt vmcnt(5)
	v_mfma_f32_16x16x32_bf16 v[74:77], v[24:27], v[32:35], 0
	v_mfma_f32_16x16x32_bf16 v[78:81], v[24:27], v[40:43], 0
	v_mfma_f32_16x16x32_bf16 v[82:85], v[24:27], v[48:51], 0
	v_mfma_f32_16x16x32_bf16 v[24:27], v[24:27], v[56:59], 0
	s_waitcnt vmcnt(4)
	v_mfma_f32_16x16x32_bf16 v[32:35], v[28:31], v[32:35], 0
	v_mfma_f32_16x16x32_bf16 v[40:43], v[28:31], v[40:43], 0
	v_mfma_f32_16x16x32_bf16 v[48:51], v[28:31], v[48:51], 0
	v_mfma_f32_16x16x32_bf16 v[28:31], v[28:31], v[56:59], 0
	ds_read_b128 v[56:59], v217 offset:64
	s_waitcnt vmcnt(3) lgkmcnt(0)
	v_mfma_f32_16x16x32_bf16 v[36:39], v[86:89], v[56:59], v[36:39]
	v_mfma_f32_16x16x32_bf16 v[44:47], v[86:89], v[90:93], v[44:47]
	v_mfma_f32_16x16x32_bf16 v[52:55], v[86:89], v[94:97], v[52:55]
	v_mfma_f32_16x16x32_bf16 v[16:19], v[86:89], v[98:101], v[16:19]
	s_waitcnt vmcnt(2)
	v_mfma_f32_16x16x32_bf16 v[60:63], v[242:245], v[56:59], v[60:63]
	v_mfma_f32_16x16x32_bf16 v[64:67], v[242:245], v[90:93], v[64:67]
	v_mfma_f32_16x16x32_bf16 v[70:73], v[242:245], v[94:97], v[70:73]
	v_mfma_f32_16x16x32_bf16 v[20:23], v[242:245], v[98:101], v[20:23]
	s_waitcnt vmcnt(1)
	v_mfma_f32_16x16x32_bf16 v[74:77], v[246:249], v[56:59], v[74:77]
	v_mfma_f32_16x16x32_bf16 v[78:81], v[246:249], v[90:93], v[78:81]
	v_mfma_f32_16x16x32_bf16 v[82:85], v[246:249], v[94:97], v[82:85]
	v_mfma_f32_16x16x32_bf16 v[24:27], v[246:249], v[98:101], v[24:27]
	s_waitcnt vmcnt(0)
	v_mfma_f32_16x16x32_bf16 v[32:35], v[250:253], v[56:59], v[32:35]
	global_load_dwordx4 v[56:59], v[68:69], off offset:128
	global_load_dwordx4 v[242:245], v[130:131], off offset:128
	global_load_dwordx4 v[246:249], v[128:129], off offset:128
	v_mfma_f32_16x16x32_bf16 v[40:43], v[250:253], v[90:93], v[40:43]
	ds_read_b128 v[90:93], v217 offset:8576
	v_mfma_f32_16x16x32_bf16 v[48:51], v[250:253], v[94:97], v[48:51]
	ds_read_b128 v[94:97], v217 offset:17024
	v_mfma_f32_16x16x32_bf16 v[28:31], v[250:253], v[98:101], v[28:31]
	global_load_dwordx4 v[250:253], v[126:127], off offset:128
	ds_read_b128 v[86:89], v217 offset:128
	ds_read_b128 v[98:101], v236 offset:128
	s_waitcnt vmcnt(3) lgkmcnt(1)
	v_mfma_f32_16x16x32_bf16 v[36:39], v[56:59], v[86:89], v[36:39]
	v_mfma_f32_16x16x32_bf16 v[44:47], v[56:59], v[90:93], v[44:47]
	v_mfma_f32_16x16x32_bf16 v[52:55], v[56:59], v[94:97], v[52:55]
	s_waitcnt lgkmcnt(0)
	v_mfma_f32_16x16x32_bf16 v[16:19], v[56:59], v[98:101], v[16:19]
	s_waitcnt vmcnt(2)
	v_mfma_f32_16x16x32_bf16 v[60:63], v[242:245], v[86:89], v[60:63]
	v_mfma_f32_16x16x32_bf16 v[64:67], v[242:245], v[90:93], v[64:67]
	v_mfma_f32_16x16x32_bf16 v[70:73], v[242:245], v[94:97], v[70:73]
	v_mfma_f32_16x16x32_bf16 v[20:23], v[242:245], v[98:101], v[20:23]
	s_waitcnt vmcnt(1)
	v_mfma_f32_16x16x32_bf16 v[74:77], v[246:249], v[86:89], v[74:77]
	v_mfma_f32_16x16x32_bf16 v[78:81], v[246:249], v[90:93], v[78:81]
	v_mfma_f32_16x16x32_bf16 v[82:85], v[246:249], v[94:97], v[82:85]
	v_mfma_f32_16x16x32_bf16 v[24:27], v[246:249], v[98:101], v[24:27]
	s_waitcnt vmcnt(0)
	v_mfma_f32_16x16x32_bf16 v[32:35], v[250:253], v[86:89], v[32:35]
	global_load_dwordx4 v[86:89], v[68:69], off offset:192
	global_load_dwordx4 v[242:245], v[130:131], off offset:192
	global_load_dwordx4 v[246:249], v[128:129], off offset:192
	v_mfma_f32_16x16x32_bf16 v[40:43], v[250:253], v[90:93], v[40:43]
	ds_read_b128 v[90:93], v217 offset:8640
	v_mfma_f32_16x16x32_bf16 v[48:51], v[250:253], v[94:97], v[48:51]
	ds_read_b128 v[94:97], v217 offset:17088
	v_mfma_f32_16x16x32_bf16 v[28:31], v[250:253], v[98:101], v[28:31]
	global_load_dwordx4 v[250:253], v[126:127], off offset:192
	ds_read_b128 v[56:59], v217 offset:192
	ds_read_b128 v[98:101], v236 offset:192
	s_waitcnt vmcnt(3) lgkmcnt(1)
; #define LAS __attribute__((address_space(3)))
; __device__ __forceinline__ void ret_out_phase(int j, LAS unsigned char* lds, int tid, int lane, int wave, int dry) { KARGS;
;     ...
;         const bf16_t* sp = ST + ((size_t)(cs * 8 + h) * 512 + 64 * wave + fr) * 256 + 8 * fq;
;         bf16x8 af[2][4];
; #pragma unroll
;         for (int et = 0; et < 4; ++et) af[0][et] = *(const bf16x8*)(sp + (size_t)et * 16 * 256);
;         __syncthreads();
;         f32x4 acc[4][4];
; #pragma unroll
;         for (int et = 0; et < 4; ++et)
; #pragma unroll
;             for (int lt = 0; lt < 4; ++lt) acc[et][lt] = (f32x4){0.f, 0.f, 0.f, 0.f};
;         {
; #pragma unroll
;             for (int ks = 0; ks < 8; ++ks) {
;                 if (ks < 7) {
; #pragma unroll
;                     for (int et = 0; et < 4; ++et) af[(ks + 1) & 1][et] = *(const bf16x8*)(sp + (size_t)et * 16 * 256 + 32 * (ks + 1));
;                 }
;                 bf16x8 qf[4];
; #pragma unroll
;                 for (int lt = 0; lt < 4; ++lt) qf[lt] = *(const LAS bf16x8*)(Ql + (16 * lt + fr) * QPITCH + (32 * ks + 8 * fq) * 2);
; #pragma unroll
;                 for (int et = 0; et < 4; ++et)
; #pragma unroll
;                     for (int lt = 0; lt < 4; ++lt) acc[et][lt] = __builtin_amdgcn_mfma_f32_16x16x32_bf16(af[ks & 1][et], qf[lt], acc[et][lt], 0, 0, 0);
;             }
	v_mfma_f32_16x16x32_bf16 v[36:39], v[86:89], v[56:59], v[36:39]
	v_mfma_f32_16x16x32_bf16 v[44:47], v[86:89], v[90:93], v[44:47]
	v_mfma_f32_16x16x32_bf16 v[52:55], v[86:89], v[94:97], v[52:55]
	s_waitcnt lgkmcnt(0)
	v_mfma_f32_16x16x32_bf16 v[16:19], v[86:89], v[98:101], v[16:19]
	s_waitcnt vmcnt(2)
	v_mfma_f32_16x16x32_bf16 v[60:63], v[242:245], v[56:59], v[60:63]
	v_mfma_f32_16x16x32_bf16 v[64:67], v[242:245], v[90:93], v[64:67]
	v_mfma_f32_16x16x32_bf16 v[70:73], v[242:245], v[94:97], v[70:73]
	v_mfma_f32_16x16x32_bf16 v[20:23], v[242:245], v[98:101], v[20:23]
	s_waitcnt vmcnt(1)
	v_mfma_f32_16x16x32_bf16 v[74:77], v[246:249], v[56:59], v[74:77]
	v_mfma_f32_16x16x32_bf16 v[78:81], v[246:249], v[90:93], v[78:81]
	v_mfma_f32_16x16x32_bf16 v[82:85], v[246:249], v[94:97], v[82:85]
	v_mfma_f32_16x16x32_bf16 v[24:27], v[246:249], v[98:101], v[24:27]
	s_waitcnt vmcnt(0)
	v_mfma_f32_16x16x32_bf16 v[32:35], v[250:253], v[56:59], v[32:35]
	global_load_dwordx4 v[56:59], v[68:69], off offset:256
	global_load_dwordx4 v[242:245], v[130:131], off offset:256
	global_load_dwordx4 v[246:249], v[128:129], off offset:256
	v_mfma_f32_16x16x32_bf16 v[40:43], v[250:253], v[90:93], v[40:43]
	ds_read_b128 v[90:93], v217 offset:8704
	v_mfma_f32_16x16x32_bf16 v[48:51], v[250:253], v[94:97], v[48:51]
	ds_read_b128 v[94:97], v217 offset:17152
	v_mfma_f32_16x16x32_bf16 v[28:31], v[250:253], v[98:101], v[28:31]
	global_load_dwordx4 v[250:253], v[126:127], off offset:256
	ds_read_b128 v[86:89], v217 offset:256
	ds_read_b128 v[98:101], v236 offset:256
	s_waitcnt vmcnt(3) lgkmcnt(1)
	v_mfma_f32_16x16x32_bf16 v[36:39], v[56:59], v[86:89], v[36:39]
	v_mfma_f32_16x16x32_bf16 v[44:47], v[56:59], v[90:93], v[44:47]
	v_mfma_f32_16x16x32_bf16 v[52:55], v[56:59], v[94:97], v[52:55]
	s_waitcnt lgkmcnt(0)
	v_mfma_f32_16x16x32_bf16 v[16:19], v[56:59], v[98:101], v[16:19]
	s_waitcnt vmcnt(2)
	v_mfma_f32_16x16x32_bf16 v[60:63], v[242:245], v[86:89], v[60:63]
	v_mfma_f32_16x16x32_bf16 v[64:67], v[242:245], v[90:93], v[64:67]
	v_mfma_f32_16x16x32_bf16 v[70:73], v[242:245], v[94:97], v[70:73]
	v_mfma_f32_16x16x32_bf16 v[20:23], v[242:245], v[98:101], v[20:23]
	s_waitcnt vmcnt(1)
	v_mfma_f32_16x16x32_bf16 v[74:77], v[246:249], v[86:89], v[74:77]
	v_mfma_f32_16x16x32_bf16 v[78:81], v[246:249], v[90:93], v[78:81]
	v_mfma_f32_16x16x32_bf16 v[82:85], v[246:249], v[94:97], v[82:85]
	v_mfma_f32_16x16x32_bf16 v[24:27], v[246:249], v[98:101], v[24:27]
	s_waitcnt vmcnt(0)
	v_mfma_f32_16x16x32_bf16 v[32:35], v[250:253], v[86:89], v[32:35]
	global_load_dwordx4 v[86:89], v[68:69], off offset:320
	v_mfma_f32_16x16x32_bf16 v[40:43], v[250:253], v[90:93], v[40:43]
	ds_read_b128 v[90:93], v217 offset:8768
	v_mfma_f32_16x16x32_bf16 v[48:51], v[250:253], v[94:97], v[48:51]
	ds_read_b128 v[94:97], v217 offset:17216
	v_mfma_f32_16x16x32_bf16 v[28:31], v[250:253], v[98:101], v[28:31]
	ds_read_b128 v[56:59], v217 offset:320
	ds_read_b128 v[98:101], v236 offset:320
	s_waitcnt vmcnt(0) lgkmcnt(1)
	v_mfma_f32_16x16x32_bf16 v[36:39], v[86:89], v[56:59], v[36:39]
	v_mfma_f32_16x16x32_bf16 v[44:47], v[86:89], v[90:93], v[44:47]
	v_mfma_f32_16x16x32_bf16 v[52:55], v[86:89], v[94:97], v[52:55]
	s_waitcnt lgkmcnt(0)
	v_mfma_f32_16x16x32_bf16 v[16:19], v[86:89], v[98:101], v[16:19]
	global_load_dwordx4 v[86:89], v[130:131], off offset:320
	s_waitcnt vmcnt(0)
	v_mfma_f32_16x16x32_bf16 v[102:105], v[86:89], v[56:59], v[60:63]
	s_nop 2
	global_load_dwordx4 v[60:63], v[128:129], off offset:320
	s_waitcnt vmcnt(0)
	v_mfma_f32_16x16x32_bf16 v[74:77], v[60:63], v[56:59], v[74:77]
	v_mfma_f32_16x16x32_bf16 v[78:81], v[60:63], v[90:93], v[78:81]
	v_mfma_f32_16x16x32_bf16 v[82:85], v[60:63], v[94:97], v[82:85]
	v_mfma_f32_16x16x32_bf16 v[24:27], v[60:63], v[98:101], v[24:27]
	global_load_dwordx4 v[60:63], v[126:127], off offset:320
	s_waitcnt vmcnt(0)
	v_mfma_f32_16x16x32_bf16 v[134:137], v[60:63], v[94:97], v[48:51]
	s_nop 2
	global_load_dwordx4 v[48:51], v[68:69], off offset:384
	v_mfma_f32_16x16x32_bf16 v[108:111], v[60:63], v[56:59], v[32:35]
	v_mfma_f32_16x16x32_bf16 v[112:115], v[60:63], v[90:93], v[40:43]
	v_mfma_f32_16x16x32_bf16 v[28:31], v[60:63], v[98:101], v[28:31]
	ds_read_b128 v[60:63], v236 offset:384
	s_waitcnt vmcnt(0)
	v_mfma_f32_16x16x32_bf16 v[40:43], v[48:51], v[146:149], v[52:55]
	s_waitcnt lgkmcnt(0)
	v_mfma_f32_16x16x32_bf16 v[52:55], v[48:51], v[60:63], v[16:19]
	s_nop 2
	global_load_dwordx4 v[16:19], v[130:131], off offset:384
	v_mfma_f32_16x16x32_bf16 v[64:67], v[86:89], v[90:93], v[64:67]
	v_mfma_f32_16x16x32_bf16 v[70:73], v[86:89], v[94:97], v[70:73]
	v_mfma_f32_16x16x32_bf16 v[20:23], v[86:89], v[98:101], v[20:23]
	s_waitcnt vmcnt(0)
	v_mfma_f32_16x16x32_bf16 v[56:59], v[16:19], v[138:141], v[102:105]
	v_mfma_f32_16x16x32_bf16 v[96:99], v[16:19], v[142:145], v[64:67]
	v_mfma_f32_16x16x32_bf16 v[100:103], v[16:19], v[146:149], v[70:73]
	s_nop 1
	global_load_dwordx4 v[64:67], v[126:127], off offset:384
	v_mfma_f32_16x16x32_bf16 v[104:107], v[16:19], v[60:63], v[20:23]
	global_load_dwordx4 v[16:19], v[128:129], off offset:384
	v_mfma_f32_16x16x32_bf16 v[32:35], v[48:51], v[138:141], v[36:39]
	v_mfma_f32_16x16x32_bf16 v[36:39], v[48:51], v[142:145], v[44:47]
	s_waitcnt vmcnt(0)
; #define LAS __attribute__((address_space(3)))
; __device__ __forceinline__ void ret_out_phase(int j, LAS unsigned char* lds, int tid, int lane, int wave, int dry) { KARGS;
;     ...
;             for (int ks = 0; ks < 8; ++ks) {
;                 if (ks < 7) {
; #pragma unroll
;                     for (int et = 0; et < 4; ++et) af[(ks + 1) & 1][et] = *(const bf16x8*)(sp + (size_t)et * 16 * 256 + 32 * (ks + 1));
;                 }
;                 bf16x8 qf[4];
; #pragma unroll
;                 for (int lt = 0; lt < 4; ++lt) qf[lt] = *(const LAS bf16x8*)(Ql + (16 * lt + fr) * QPITCH + (32 * ks + 8 * fq) * 2);
; #pragma unroll
;                 for (int et = 0; et < 4; ++et)
; #pragma unroll
;                     for (int lt = 0; lt < 4; ++lt) acc[et][lt] = __builtin_amdgcn_mfma_f32_16x16x32_bf16(af[ks & 1][et], qf[lt], acc[et][lt], 0, 0, 0);
;             }
;         }
; #pragma unroll
;         for (int lt = 0; lt < 4; ++lt) { const float cr = exp2f((float)(16 * lt + fr + 1 + (odd ? 64 : 0)) * l2g);
; #pragma unroll
;             for (int et = 0; et < 4; ++et) acc[et][lt] *= cr; }
;         {
;             const bf16_t* vp = VT + ((size_t)(c * 8 + h) * 512 + 64 * wave + fr) * 64 + 8 * fq;
; #pragma unroll
;             for (int ks = 0; ks < 2; ++ks) {
;                 bf16x8 vf[4], pf[4];
; #pragma unroll
;                 for (int et = 0; et < 4; ++et) vf[et] = *(const bf16x8*)(vp + (size_t)et * 16 * 64 + 32 * ks);
; #pragma unroll
;                 for (int lt = 0; lt < 4; ++lt) pf[lt] = *(const LAS bf16x8*)(Pl + (16 * lt + fr) * PPITCH + (32 * ks + 8 * fq) * 2);
; #pragma unroll
;                 for (int et = 0; et < 4; ++et)
; #pragma unroll
;                     for (int lt = 0; lt < 4; ++lt) acc[et][lt] = __builtin_amdgcn_mfma_f32_16x16x32_bf16(vf[et], pf[lt], acc[et][lt], 0, 0, 0);
	v_mfma_f32_16x16x32_bf16 v[44:47], v[16:19], v[138:141], v[74:77]
	v_mfma_f32_16x16x32_bf16 v[48:51], v[16:19], v[142:145], v[78:81]
	v_mfma_f32_16x16x32_bf16 v[88:91], v[16:19], v[146:149], v[82:85]
	v_mfma_f32_16x16x32_bf16 v[92:95], v[16:19], v[60:63], v[24:27]
	s_nop 1
	ds_read_b128 v[84:87], v217 offset:17344
	ds_read_b128 v[80:83], v236 offset:448
	v_mfma_f32_16x16x32_bf16 v[16:19], v[64:67], v[146:149], v[134:137]
	s_nop 2
	global_load_dwordx4 v[134:137], v[68:69], off offset:448
	v_mfma_f32_16x16x32_bf16 v[76:79], v[64:67], v[60:63], v[28:31]
	s_nop 2
	global_load_dwordx4 v[28:31], v[130:131], off offset:448
	v_mfma_f32_16x16x32_bf16 v[20:23], v[64:67], v[138:141], v[108:111]
	ds_read_b128 v[138:141], v239 offset:38400
	v_mfma_f32_16x16x32_bf16 v[24:27], v[64:67], v[142:145], v[112:115]
	s_nop 0
	ds_read_b128 v[108:111], v217 offset:448
	s_nop 0
	ds_read_b128 v[112:115], v217 offset:8896
	s_waitcnt vmcnt(1) lgkmcnt(0)
	v_mfma_f32_16x16x32_bf16 v[68:71], v[134:137], v[112:115], v[36:39]
	s_waitcnt vmcnt(0)
	v_mfma_f32_16x16x32_bf16 v[36:39], v[28:31], v[112:115], v[96:99]
	s_nop 2
	global_load_dwordx4 v[96:99], v[128:129], off offset:448
	v_mfma_f32_16x16x32_bf16 v[64:67], v[134:137], v[84:87], v[40:43]
	ds_read_b128 v[128:131], v239 offset:33792
	v_mfma_f32_16x16x32_bf16 v[40:43], v[28:31], v[108:111], v[56:59]
	s_waitcnt vmcnt(0)
	v_mfma_f32_16x16x32_bf16 v[56:59], v[96:99], v[108:111], v[44:47]
	v_mfma_f32_16x16x32_bf16 v[44:47], v[96:99], v[80:83], v[92:95]
	s_nop 2
	global_load_dwordx4 v[92:95], v[126:127], off offset:448
	v_mfma_f32_16x16x32_bf16 v[60:63], v[134:137], v[80:83], v[52:55]
	v_mfma_f32_16x16x32_bf16 v[52:55], v[96:99], v[112:115], v[48:51]
	v_mfma_f32_16x16x32_bf16 v[48:51], v[96:99], v[84:87], v[88:91]
	s_waitcnt vmcnt(0)
	v_mfma_f32_16x16x32_bf16 v[88:91], v[92:95], v[108:111], v[20:23]
	v_mfma_f32_16x16x32_bf16 v[20:23], v[92:95], v[112:115], v[24:27]
	v_lshl_add_u64 v[112:113], v[120:121], 0, s[4:5]
	global_load_dwordx4 v[96:99], v[112:113], off
	v_mfma_f32_16x16x32_bf16 v[72:75], v[134:137], v[108:111], v[32:35]
	ds_read_b128 v[134:137], v239 offset:36096
	v_mfma_f32_16x16x32_bf16 v[32:35], v[28:31], v[84:87], v[100:103]
	v_mfma_f32_16x16x32_bf16 v[108:111], v[92:95], v[84:87], v[16:19]
	v_or_b32_e32 v84, s18, v186
	s_nop 1
	v_cvt_f32_ubyte0_e32 v16, v84
	v_mul_f32_e32 v17, v132, v16
	v_cmp_gt_f32_e32 vcc, s82, v17
	v_mfma_f32_16x16x32_bf16 v[28:31], v[28:31], v[80:83], v[104:107]
	s_nop 0
	v_cndmask_b32_e32 v17, 0, v234, vcc
	v_fmac_f32_e32 v17, v132, v16
	v_exp_f32_e32 v16, v17
	v_cndmask_b32_e32 v17, 0, v230, vcc
	v_mfma_f32_16x16x32_bf16 v[76:79], v[92:95], v[80:83], v[76:79]
	v_ldexp_f32 v142, v16, v17
	v_add_u32_e32 v16, 16, v84
	v_cvt_f32_ubyte0_e32 v16, v16
	v_mul_f32_e32 v17, v132, v16
	v_cmp_gt_f32_e32 vcc, s82, v17
	v_pk_mul_f32 v[18:19], v[142:143], v[74:75] op_sel_hi:[0,1]
	v_pk_mul_f32 v[42:43], v[142:143], v[42:43] op_sel_hi:[0,1]
	v_cndmask_b32_e32 v17, 0, v234, vcc
	v_fmac_f32_e32 v17, v132, v16
	v_exp_f32_e32 v24, v17
	v_cndmask_b32_e32 v25, 0, v230, vcc
	v_pk_mul_f32 v[16:17], v[142:143], v[72:73] op_sel_hi:[0,1]
	v_pk_mul_f32 v[40:41], v[142:143], v[40:41] op_sel_hi:[0,1]
	v_ldexp_f32 v144, v24, v25
	v_or_b32_e32 v24, 32, v84
	v_cvt_f32_ubyte0_e32 v24, v24
	v_mul_f32_e32 v25, v132, v24
	v_cmp_gt_f32_e32 vcc, s82, v25
	v_pk_mul_f32 v[26:27], v[144:145], v[70:71] op_sel_hi:[0,1]
	v_pk_mul_f32 v[38:39], v[144:145], v[38:39] op_sel_hi:[0,1]
	v_cndmask_b32_e32 v25, 0, v234, vcc
	v_fmac_f32_e32 v25, v132, v24
	v_exp_f32_e32 v72, v25
	v_pk_mul_f32 v[24:25], v[144:145], v[68:69] op_sel_hi:[0,1]
	v_cndmask_b32_e32 v68, 0, v230, vcc
	v_pk_mul_f32 v[36:37], v[144:145], v[36:37] op_sel_hi:[0,1]
	v_ldexp_f32 v146, v72, v68
	v_pk_mul_f32 v[80:81], v[146:147], v[64:65] op_sel_hi:[0,1]
	v_add_u32_e32 v64, 48, v84
	v_cvt_f32_ubyte0_e32 v64, v64
	v_mul_f32_e32 v65, v132, v64
	v_cmp_gt_f32_e32 vcc, s82, v65
	s_waitcnt vmcnt(0) lgkmcnt(1)
	v_mfma_f32_16x16x32_bf16 v[68:71], v[96:99], v[128:131], v[16:19]
	s_nop 2
	v_cndmask_b32_e32 v16, 0, v234, vcc
	v_fmac_f32_e32 v16, v132, v64
	v_exp_f32_e32 v16, v16
	v_cndmask_b32_e32 v17, 0, v230, vcc
	ds_read_b128 v[72:75], v240 offset:33792
	v_add_co_u32_e32 v114, vcc, s83, v112
	v_ldexp_f32 v126, v16, v17
	v_pk_mul_f32 v[18:19], v[126:127], v[62:63] op_sel_hi:[0,1]
	v_pk_mul_f32 v[16:17], v[126:127], v[60:61] op_sel_hi:[0,1]
	global_load_dwordx4 v[60:63], v[112:113], off offset:2048
	v_pk_mul_f32 v[82:83], v[146:147], v[66:67] op_sel_hi:[0,1]
	v_addc_co_u32_e32 v115, vcc, 0, v113, vcc
	s_waitcnt lgkmcnt(1)
	v_mfma_f32_16x16x32_bf16 v[64:67], v[96:99], v[134:137], v[24:27]
	v_mul_f32_e64 v46, v126, v46
	v_mul_f32_e64 v47, v126, v47
	v_pk_mul_f32 v[44:45], v[126:127], v[44:45] op_sel_hi:[0,1]
	v_pk_mul_f32 v[50:51], v[146:147], v[50:51] op_sel_hi:[0,1]
	v_mfma_f32_16x16x32_bf16 v[24:27], v[96:99], v[138:141], v[80:83]
	v_mul_f32_e64 v48, v146, v48
	v_mul_f32_e64 v49, v146, v49
	v_pk_mul_f32 v[30:31], v[126:127], v[30:31] op_sel_hi:[0,1]
	v_pk_mul_f32 v[28:29], v[126:127], v[28:29] op_sel_hi:[0,1]
	s_waitcnt lgkmcnt(0)
	v_mfma_f32_16x16x32_bf16 v[16:19], v[96:99], v[72:75], v[16:19]
	v_mul_f32_e64 v22, v144, v22
	v_mul_f32_e64 v23, v144, v23
	v_pk_mul_f32 v[20:21], v[144:145], v[20:21] op_sel_hi:[0,1]
	v_pk_mul_f32 v[34:35], v[146:147], v[34:35] op_sel_hi:[0,1]
	s_waitcnt vmcnt(0)
	v_mfma_f32_16x16x32_bf16 v[96:99], v[60:63], v[128:131], v[40:43]
	s_nop 2
	global_load_dwordx4 v[40:43], v[114:115], off
	v_pk_mul_f32 v[32:33], v[146:147], v[32:33] op_sel_hi:[0,1]
	s_and_b64 vcc, exec, s[8:9]
	s_waitcnt vmcnt(0)
; #define LAS __attribute__((address_space(3)))
; __device__ __forceinline__ void ret_out_phase(int j, LAS unsigned char* lds, int tid, int lane, int wave, int dry) { KARGS;
;     ...
;         for (int lt = 0; lt < 4; ++lt) { const float cr = exp2f((float)(16 * lt + fr + 1 + (odd ? 64 : 0)) * l2g);
; #pragma unroll
;             for (int et = 0; et < 4; ++et) acc[et][lt] *= cr; }
;         {
;             const bf16_t* vp = VT + ((size_t)(c * 8 + h) * 512 + 64 * wave + fr) * 64 + 8 * fq;
; #pragma unroll
;             for (int ks = 0; ks < 2; ++ks) {
;                 bf16x8 vf[4], pf[4];
; #pragma unroll
;                 for (int et = 0; et < 4; ++et) vf[et] = *(const bf16x8*)(vp + (size_t)et * 16 * 64 + 32 * ks);
; #pragma unroll
;                 for (int lt = 0; lt < 4; ++lt) pf[lt] = *(const LAS bf16x8*)(Pl + (16 * lt + fr) * PPITCH + (32 * ks + 8 * fq) * 2);
; #pragma unroll
;                 for (int et = 0; et < 4; ++et)
; #pragma unroll
;                     for (int lt = 0; lt < 4; ++lt) acc[et][lt] = __builtin_amdgcn_mfma_f32_16x16x32_bf16(vf[et], pf[lt], acc[et][lt], 0, 0, 0);
;             }
;             if (odd) {
;                 const bf16_t* vp2 = vp - (size_t)8 * 512 * 64;
; #pragma unroll
;                 for (int ks = 0; ks < 2; ++ks) {
;                     bf16x8 vf[4], pf[4];
; #pragma unroll
;                     for (int et = 0; et < 4; ++et) vf[et] = *(const bf16x8*)(vp2 + (size_t)et * 16 * 64 + 32 * ks);
; #pragma unroll
;                     for (int lt = 0; lt < 4; ++lt) pf[lt] = *(const LAS bf16x8*)(Pl2 + (16 * lt + fr) * PPITCH + (32 * ks + 8 * fq) * 2);
; #pragma unroll
;                     for (int et = 0; et < 4; ++et)
; #pragma unroll
;                         for (int lt = 0; lt < 4; ++lt) acc[et][lt] = __builtin_amdgcn_mfma_f32_16x16x32_bf16(vf[et], pf[lt], acc[et][lt], 0, 0, 0);
;                 }
;             }
	v_mfma_f32_16x16x32_bf16 v[92:95], v[40:43], v[72:75], v[44:47]
	s_nop 2
	global_load_dwordx4 v[44:47], v[114:115], off offset:2048
	v_mfma_f32_16x16x32_bf16 v[84:87], v[40:43], v[138:141], v[48:51]
	s_nop 2
	global_load_dwordx4 v[48:51], v[112:113], off offset:64
	v_mfma_f32_16x16x32_bf16 v[100:103], v[60:63], v[134:137], v[36:39]
	v_mfma_f32_16x16x32_bf16 v[104:107], v[60:63], v[72:75], v[28:31]
	s_nop 1
	v_mul_f32_e64 v38, v144, v54
	v_mul_f32_e64 v39, v144, v55
	v_pk_mul_f32 v[36:37], v[144:145], v[52:53] op_sel_hi:[0,1]
	v_pk_mul_f32 v[30:31], v[142:143], v[58:59] op_sel_hi:[0,1]
	v_pk_mul_f32 v[28:29], v[142:143], v[56:57] op_sel_hi:[0,1]
	v_mfma_f32_16x16x32_bf16 v[36:39], v[40:43], v[134:137], v[36:39]
	s_nop 0
	v_mfma_f32_16x16x32_bf16 v[28:31], v[40:43], v[128:131], v[28:31]
	v_mul_f32_e64 v42, v142, v90
	v_mul_f32_e64 v43, v142, v91
	v_pk_mul_f32 v[40:41], v[142:143], v[88:89] op_sel_hi:[0,1]
	s_waitcnt vmcnt(1)
	v_mfma_f32_16x16x32_bf16 v[52:55], v[44:47], v[134:137], v[20:23]
	s_nop 2
	v_mul_f32_e64 v22, v146, v110
	v_mul_f32_e64 v23, v146, v111
	v_pk_mul_f32 v[20:21], v[146:147], v[108:109] op_sel_hi:[0,1]
	ds_read_b128 v[108:111], v239 offset:36160
	v_mfma_f32_16x16x32_bf16 v[40:43], v[44:47], v[128:131], v[40:43]
	ds_read_b128 v[130:133], v240 offset:33856
	v_mfma_f32_16x16x32_bf16 v[80:83], v[44:47], v[138:141], v[20:23]
	s_nop 2
	v_mul_f32_e64 v22, v126, v78
	v_mul_f32_e64 v23, v126, v79
	v_pk_mul_f32 v[20:21], v[126:127], v[76:77] op_sel_hi:[0,1]
	ds_read_b128 v[126:129], v239 offset:38464
	v_mfma_f32_16x16x32_bf16 v[32:35], v[60:63], v[138:141], v[32:35]
	ds_read_b128 v[76:79], v239 offset:33856
	s_waitcnt vmcnt(0) lgkmcnt(2)
	v_mfma_f32_16x16x32_bf16 v[60:63], v[48:51], v[130:133], v[16:19]
	s_nop 2
	global_load_dwordx4 v[16:19], v[112:113], off offset:2112
	v_mfma_f32_16x16x32_bf16 v[88:91], v[44:47], v[72:75], v[20:23]
	s_waitcnt lgkmcnt(0)
	v_mfma_f32_16x16x32_bf16 v[20:23], v[48:51], v[76:79], v[68:71]
	v_mfma_f32_16x16x32_bf16 v[68:71], v[48:51], v[126:129], v[24:27]
	s_waitcnt vmcnt(0)
	v_mfma_f32_16x16x32_bf16 v[56:59], v[16:19], v[76:79], v[96:99]
	v_mfma_f32_16x16x32_bf16 v[44:47], v[16:19], v[108:111], v[100:103]
	v_mfma_f32_16x16x32_bf16 v[32:35], v[16:19], v[126:129], v[32:35]
	v_mfma_f32_16x16x32_bf16 v[24:27], v[16:19], v[130:133], v[104:107]
	global_load_dwordx4 v[16:19], v[114:115], off offset:64
	v_mfma_f32_16x16x32_bf16 v[72:75], v[48:51], v[108:111], v[64:67]
	s_waitcnt vmcnt(0)
	v_mfma_f32_16x16x32_bf16 v[48:51], v[16:19], v[76:79], v[28:31]
	v_mfma_f32_16x16x32_bf16 v[28:31], v[16:19], v[126:129], v[84:87]
	s_nop 2
	global_load_dwordx4 v[84:87], v[114:115], off offset:2112
	v_mfma_f32_16x16x32_bf16 v[36:39], v[16:19], v[108:111], v[36:39]
	v_mfma_f32_16x16x32_bf16 v[16:19], v[16:19], v[130:133], v[92:95]
	s_waitcnt vmcnt(0)
	v_mfma_f32_16x16x32_bf16 v[76:79], v[84:87], v[76:79], v[40:43]
	v_mfma_f32_16x16x32_bf16 v[64:67], v[84:87], v[108:111], v[52:55]
	v_mfma_f32_16x16x32_bf16 v[52:55], v[84:87], v[126:129], v[80:83]
	v_mfma_f32_16x16x32_bf16 v[40:43], v[84:87], v[130:133], v[88:91]
	s_cbranch_vccnz .LBB0_779
	s_nop 0
	v_add_co_u32_e32 v80, vcc, 0xfff80000, v112
	ds_read_b128 v[84:87], v239 offset:43008
	s_nop 0
	v_addc_co_u32_e32 v81, vcc, -1, v113, vcc
	global_load_dwordx4 v[80:83], v[80:81], off
	ds_read_b128 v[88:91], v239 offset:45312
	ds_read_b128 v[92:95], v239 offset:47616
	ds_read_b128 v[96:99], v240 offset:43008
	v_add_co_u32_e32 v100, vcc, 0xfff81000, v112
	s_waitcnt vmcnt(0) lgkmcnt(3)
	v_mfma_f32_16x16x32_bf16 v[20:23], v[80:83], v[84:87], v[20:23]
	v_addc_co_u32_e32 v101, vcc, -1, v113, vcc
	v_add_co_u32_e32 v102, vcc, 0xfff82000, v112
	s_waitcnt lgkmcnt(2)
	v_mfma_f32_16x16x32_bf16 v[72:75], v[80:83], v[88:91], v[72:75]
	v_addc_co_u32_e32 v103, vcc, -1, v113, vcc
	s_waitcnt lgkmcnt(1)
	v_mfma_f32_16x16x32_bf16 v[68:71], v[80:83], v[92:95], v[68:71]
	s_waitcnt lgkmcnt(0)
	v_mfma_f32_16x16x32_bf16 v[60:63], v[80:83], v[96:99], v[60:63]
	global_load_dwordx4 v[80:83], v[100:101], off offset:-2048
	s_waitcnt vmcnt(0)
	v_mfma_f32_16x16x32_bf16 v[56:59], v[80:83], v[84:87], v[56:59]
	v_mfma_f32_16x16x32_bf16 v[44:47], v[80:83], v[88:91], v[44:47]
	v_mfma_f32_16x16x32_bf16 v[32:35], v[80:83], v[92:95], v[32:35]
	v_mfma_f32_16x16x32_bf16 v[24:27], v[80:83], v[96:99], v[24:27]
	global_load_dwordx4 v[80:83], v[100:101], off
	s_waitcnt vmcnt(0)
	v_mfma_f32_16x16x32_bf16 v[48:51], v[80:83], v[84:87], v[48:51]
	v_mfma_f32_16x16x32_bf16 v[36:39], v[80:83], v[88:91], v[36:39]
	v_mfma_f32_16x16x32_bf16 v[28:31], v[80:83], v[92:95], v[28:31]
	v_mfma_f32_16x16x32_bf16 v[16:19], v[80:83], v[96:99], v[16:19]
	global_load_dwordx4 v[80:83], v[102:103], off offset:-2048
	s_waitcnt vmcnt(0)
	v_mfma_f32_16x16x32_bf16 v[76:79], v[80:83], v[84:87], v[76:79]
	global_load_dwordx4 v[84:87], v[100:101], off offset:-4032
	v_mfma_f32_16x16x32_bf16 v[64:67], v[80:83], v[88:91], v[64:67]
	ds_read_b128 v[88:91], v239 offset:45376
	v_mfma_f32_16x16x32_bf16 v[52:55], v[80:83], v[92:95], v[52:55]
	ds_read_b128 v[92:95], v239 offset:47680
	v_mfma_f32_16x16x32_bf16 v[40:43], v[80:83], v[96:99], v[40:43]
	ds_read_b128 v[80:83], v239 offset:43072
	ds_read_b128 v[96:99], v240 offset:43072
	s_waitcnt vmcnt(0) lgkmcnt(1)
	v_mfma_f32_16x16x32_bf16 v[20:23], v[84:87], v[80:83], v[20:23]
	v_mfma_f32_16x16x32_bf16 v[72:75], v[84:87], v[88:91], v[72:75]
	v_mfma_f32_16x16x32_bf16 v[68:71], v[84:87], v[92:95], v[68:71]
	s_waitcnt lgkmcnt(0)
	v_mfma_f32_16x16x32_bf16 v[60:63], v[84:87], v[96:99], v[60:63]
	global_load_dwordx4 v[84:87], v[100:101], off offset:-1984
	s_waitcnt vmcnt(0)
	v_mfma_f32_16x16x32_bf16 v[56:59], v[84:87], v[80:83], v[56:59]
	v_mfma_f32_16x16x32_bf16 v[44:47], v[84:87], v[88:91], v[44:47]
	v_mfma_f32_16x16x32_bf16 v[32:35], v[84:87], v[92:95], v[32:35]
	v_mfma_f32_16x16x32_bf16 v[24:27], v[84:87], v[96:99], v[24:27]
	global_load_dwordx4 v[84:87], v[102:103], off offset:-4032
	s_waitcnt vmcnt(0)
	v_mfma_f32_16x16x32_bf16 v[48:51], v[84:87], v[80:83], v[48:51]
	v_mfma_f32_16x16x32_bf16 v[36:39], v[84:87], v[88:91], v[36:39]
	v_mfma_f32_16x16x32_bf16 v[28:31], v[84:87], v[92:95], v[28:31]
	v_mfma_f32_16x16x32_bf16 v[16:19], v[84:87], v[96:99], v[16:19]
	global_load_dwordx4 v[84:87], v[102:103], off offset:-1984
	s_waitcnt vmcnt(0)
	v_mfma_f32_16x16x32_bf16 v[76:79], v[84:87], v[80:83], v[76:79]
	v_mfma_f32_16x16x32_bf16 v[64:67], v[84:87], v[88:91], v[64:67]
	v_mfma_f32_16x16x32_bf16 v[52:55], v[84:87], v[92:95], v[52:55]
	v_mfma_f32_16x16x32_bf16 v[40:43], v[84:87], v[96:99], v[40:43]
